# speedup vs baseline: 1.0144x; 1.0144x over previous
; #define SBAR() __builtin_amdgcn_sched_barrier(0)
; __device__ __forceinline__ int v_st(int k, int c) { const int kk = (k & ~0xC) | ((k & 4) << 1) | ((k & 8) >> 1); return ((kk >> 3) * 4 + (c >> 5)) * 512 + ((kk & 7) * 32 + (c & 31)) * 2; }
; __device__ __forceinline__ int v_rd_base(int lane) { return ((lane & 3) << 3) | (((lane >> 2) & 3) << 6) | (((lane >> 4) & 1) << 5) | (((lane >> 5) & 1) << 8); }
; #define SWAIT() asm volatile("s_waitcnt vmcnt(4)" ::: "memory")
; template <bool BANDED, bool FIXED> ...
;     ...
;   float m_reg = FIXED ? 0.f : -1e30f, l_reg = 0; f32x16 o[4] = {}; bf16x8 qr[8];
;   const bf16* Qw = Qb + (wid * QBLK + r32) * ldq + hi * 8;
; #pragma unroll
;   for (int d0 = 0; d0 < 8; ++d0) qr[d0] = *reinterpret_cast<const bf16x8*>(Qw + d0 * 16);
;   const int sr = tid >> 4, sc = (tid & 15) * 8, vst0 = v_st(sr, sc), vst1 = v_st(32 + sr, sc);
;   const int vb0 = (int)(uintptr_t)V_lds + v_rd_base(lane);
;   const int qi = q0 + wid * QBLK + r32;
;   const int mlo = BANDED ? max(-64, -qi) : 0, mhi = BANDED ? min(64, L - 1 - qi) : 0;
;   const int rel00 = kt0 - qi + 4 * hi;
;   struct { bf16x8 vs0, vs1, ks0, ks1; } sr_[2];
;     ...
;   f32x16 pA0, pA1, pB0, pB1; float mnA, mnB, alA, alB; bf16x8 pa0, pa1, pa2, pa3;
;   constexpr int SE = 0, SO = 1;
;   SLOAD(SE, 0); asm volatile("s_waitcnt vmcnt(0)" ::: "memory"); SWRITE(0, SE); __syncthreads();
;   if (FIXED) qkt_c(pA0, pA1, K_lds, qr, r32, hi); else qkt(pA0, pA1, K_lds, qr, r32, hi, 0.f); MASK(pA0, pA1, 0); partialSM<FIXED, !BANDED>(pA0, pA1, m_reg, mnA, alA);
;   SLOAD(SO, 1); if (2 < NT) SLOAD(SE, 2);
;   SWAIT(); SWRITE(1, SO); __syncthreads();
;   if (!BANDED && wave >= 4) __builtin_amdgcn_s_setprio(2);
;   for (int j = 1; j + 1 < NT; j += 2) {
;     SBAR(); if (FIXED) qkt_c(pB0, pB1, (bf16*)((char*)K_lds + SHM_K), qr, r32, hi); else qkt(pB0, pB1, (bf16*)((char*)K_lds + SHM_K), qr, r32, hi, 0.f); MASK(pB0, pB1, j);
;     finishSM(pA0, pA1, alA, l_reg, pa0, pa1, pa2, pa3); SBAR();
;     SLOAD(SO, j + 2); SBAR();
;     pv_d0(o, vb0, pa0, pa1, pa2, pa3); partialSM<FIXED, !BANDED>(pB0, pB1, m_reg, mnB, alB);
;     __syncthreads(); SWAIT(); SWRITE(0, SE);
;     RESC(alB); __syncthreads();
;     SBAR(); if (FIXED) qkt_c(pA0, pA1, K_lds, qr, r32, hi); else qkt(pA0, pA1, K_lds, qr, r32, hi, 0.f); MASK(pA0, pA1, j + 1);
.LBB0_117:
	v_and_b32_e32 v19, 63, v22
	v_exp_f32_e32 v225, v3
	v_lshlrev_b32_e32 v3, 4, v19
	v_exp_f32_e32 v223, v2
	v_exp_f32_e32 v221, v4
	v_lshlrev_b32_e32 v2, 3, v19
	v_and_b32_e32 v3, 0xc0, v3
	v_lshlrev_b32_e32 v4, 1, v19
	v_exp_f32_e32 v224, v5
	v_exp_f32_e32 v220, v6
	v_exp_f32_e32 v222, v7
	v_exp_f32_e32 v218, v8
	v_exp_f32_e32 v219, v9
	v_exp_f32_e32 v215, v10
	v_exp_f32_e32 v217, v11
	v_exp_f32_e32 v214, v12
	v_exp_f32_e32 v216, v13
	v_exp_f32_e32 v210, v14
	v_exp_f32_e32 v213, v15
	v_exp_f32_e32 v211, v16
	v_exp_f32_e32 v212, v17
	v_and_or_b32 v3, v2, 24, v3
	v_and_b32_e32 v4, 32, v4
	v_and_b32_e32 v2, 0x100, v2
	s_cmp_lg_u32 0, -1
	v_or3_b32 v2, v3, v4, v2
	s_cselect_b32 s40, 0, 0
	v_add_u32_e32 v208, s40, v2
	s_addk_i32 s40, 0x4000
	v_mov_b32_e32 v183, 0
	s_mov_b32 s2, -1
	v_lshl_add_u32 v14, v18, 1, v0
	v_add_u32_e32 v15, 0x30000, v14
	v_add_u32_e32 v0, s40, v2
	v_mov_b32_e32 v16, 0
	v_mov_b32_e32 v17, v183
	v_mov_b32_e32 v18, v183
	v_mov_b32_e32 v19, v183
	v_mov_b32_e32 v20, v183
	v_mov_b32_e32 v21, v183
	v_mov_b32_e32 v22, v183
	v_mov_b32_e32 v23, v183
	v_mov_b32_e32 v24, v183
	v_mov_b32_e32 v25, v183
	v_mov_b32_e32 v26, v183
	v_mov_b32_e32 v27, v183
	v_mov_b32_e32 v28, v183
	v_mov_b32_e32 v29, v183
	v_mov_b32_e32 v30, v183
	v_mov_b32_e32 v31, v183
	v_mov_b32_e32 v32, 0
	v_mov_b32_e32 v33, v183
	v_mov_b32_e32 v34, v183
	v_mov_b32_e32 v35, v183
	v_mov_b32_e32 v36, v183
	v_mov_b32_e32 v37, v183
	v_mov_b32_e32 v38, v183
	v_mov_b32_e32 v39, v183
	v_mov_b32_e32 v40, v183
	v_mov_b32_e32 v41, v183
	v_mov_b32_e32 v42, v183
	v_mov_b32_e32 v43, v183
	v_mov_b32_e32 v44, v183
	v_mov_b32_e32 v45, v183
	v_mov_b32_e32 v46, v183
	v_mov_b32_e32 v47, v183
	v_mov_b32_e32 v48, 0
	v_mov_b32_e32 v49, v183
	v_mov_b32_e32 v50, v183
	v_mov_b32_e32 v51, v183
	v_mov_b32_e32 v52, v183
	v_mov_b32_e32 v53, v183
	v_mov_b32_e32 v54, v183
	v_mov_b32_e32 v55, v183
	v_mov_b32_e32 v56, v183
	v_mov_b32_e32 v57, v183
	v_mov_b32_e32 v58, v183
	v_mov_b32_e32 v59, v183
	v_mov_b32_e32 v60, v183
	v_mov_b32_e32 v61, v183
	v_mov_b32_e32 v62, v183
	v_mov_b32_e32 v63, v183
	v_mov_b32_e32 v64, 0
	v_mov_b32_e32 v65, v183
	v_mov_b32_e32 v66, v183
	v_mov_b32_e32 v67, v183
	v_mov_b32_e32 v68, v183
	v_mov_b32_e32 v69, v183
	v_mov_b32_e32 v70, v183
	v_mov_b32_e32 v71, v183
	v_mov_b32_e32 v72, v183
	v_mov_b32_e32 v73, v183
	v_mov_b32_e32 v74, v183
	v_mov_b32_e32 v75, v183
	v_mov_b32_e32 v76, v183
	v_mov_b32_e32 v77, v183
	v_mov_b32_e32 v78, v183
	v_mov_b32_e32 v79, v183
	s_mov_b32 vcc_lo, 0x11000
	s_mov_b32 vcc_hi, 0
	s_mov_b32 s101, 0x4000
	ds_read_b128 v[2:5], v200 offset:49152
	ds_read_b128 v[6:9], v200 offset:57344
.LBB0_118:
	s_add_i32 s2, s2, 2
	v_exp_f32_e32 v10, v88
	v_exp_f32_e32 v11, v89
	v_exp_f32_e32 v12, v90
	s_waitcnt lgkmcnt(1)
	v_mfma_f32_32x32x16_bf16 v[112:127], v[2:5], v[156:159], 0
	v_exp_f32_e32 v13, v91
	v_exp_f32_e32 v176, v92
	v_exp_f32_e32 v177, v93
	v_exp_f32_e32 v178, v94
	v_exp_f32_e32 v95, v95
	v_cvt_pk_bf16_f32 v92, v10, v11
	v_cvt_pk_bf16_f32 v93, v12, v13
	s_waitcnt lgkmcnt(0)
	v_mfma_f32_32x32x16_bf16 v[96:111], v[6:9], v[156:159], 0
	ds_read_b128 v[2:5], v201 offset:49152
	ds_read_b128 v[6:9], v201 offset:57344
	v_cvt_pk_bf16_f32 v94, v176, v177
	s_nop 0
	v_permlane32_swap_b32_e32 v92, v94
	s_waitcnt lgkmcnt(1)
	v_mfma_f32_32x32x16_bf16 v[112:127], v[2:5], v[152:155], v[112:127]
	s_waitcnt lgkmcnt(0)
	v_mfma_f32_32x32x16_bf16 v[96:111], v[6:9], v[152:155], v[96:111]
	ds_read_b128 v[2:5], v202 offset:49152
	ds_read_b128 v[6:9], v202 offset:57344
	s_waitcnt lgkmcnt(1)
	v_mfma_f32_32x32x16_bf16 v[112:127], v[2:5], v[148:151], v[112:127]
	s_waitcnt lgkmcnt(0)
	v_mfma_f32_32x32x16_bf16 v[96:111], v[6:9], v[148:151], v[96:111]
	ds_read_b128 v[2:5], v203 offset:49152
	ds_read_b128 v[6:9], v203 offset:57344
	v_add_u32_e32 v254, vcc_lo, v184
	v_add_u32_e32 v255, vcc_lo, v185
	s_waitcnt vmcnt(0)
	ds_write_b128 v254, v[160:163]
	s_waitcnt lgkmcnt(2)
	v_mfma_f32_32x32x16_bf16 v[112:127], v[2:5], v[144:147], v[112:127]
	s_waitcnt lgkmcnt(1)
	v_mfma_f32_32x32x16_bf16 v[96:111], v[6:9], v[144:147], v[96:111]
	ds_read_b128 v[2:5], v206 offset:49152
	ds_read_b128 v[6:9], v206 offset:57344
	ds_write_b128 v255, v[164:167]
	s_waitcnt lgkmcnt(2)
	v_mfma_f32_32x32x16_bf16 v[112:127], v[2:5], v[140:143], v[112:127]
	s_waitcnt lgkmcnt(1)
	v_mfma_f32_32x32x16_bf16 v[96:111], v[6:9], v[140:143], v[96:111]
	ds_read_b128 v[2:5], v204 offset:49152
	ds_read_b128 v[6:9], v204 offset:57344
	ds_write_b128 v198, v[168:171] offset:32768
	s_waitcnt lgkmcnt(2)
	v_mfma_f32_32x32x16_bf16 v[112:127], v[2:5], v[136:139], v[112:127]
	s_waitcnt lgkmcnt(1)
	v_mfma_f32_32x32x16_bf16 v[96:111], v[6:9], v[136:139], v[96:111]
	ds_read_b128 v[2:5], v205 offset:49152
	ds_read_b128 v[6:9], v205 offset:57344
	ds_write_b128 v199, v[172:175] offset:32768
	s_waitcnt lgkmcnt(2)
	v_mfma_f32_32x32x16_bf16 v[112:127], v[2:5], v[132:135], v[112:127]
	s_waitcnt lgkmcnt(1)
	v_mfma_f32_32x32x16_bf16 v[96:111], v[6:9], v[132:135], v[96:111]
	ds_read_b128 v[2:5], v207 offset:49152
	ds_read_b128 v[6:9], v207 offset:57344
	s_waitcnt lgkmcnt(1)
	v_mfma_f32_32x32x16_bf16 v[112:127], v[2:5], v[128:131], v[112:127]
	v_exp_f32_e32 v2, v80
	v_add_f32_e32 v80, 0, v223
	v_add_f32_e32 v80, v225, v80
	v_add_f32_e32 v80, v221, v80
	v_add_f32_e32 v80, v224, v80
	v_add_f32_e32 v80, v220, v80
	v_add_f32_e32 v80, v222, v80
	v_add_f32_e32 v80, v218, v80
	v_add_f32_e32 v80, v219, v80
	v_add_f32_e32 v80, v215, v80
	v_add_f32_e32 v80, v217, v80
	v_add_f32_e32 v80, v214, v80
	v_add_f32_e32 v80, v216, v80
	v_add_f32_e32 v80, v210, v80
	v_exp_f32_e32 v3, v81
	v_add_f32_e32 v80, v213, v80
	v_exp_f32_e32 v4, v82
	v_add_f32_e32 v80, v211, v80
	v_exp_f32_e32 v5, v83
	v_add_f32_e32 v80, v212, v80
	s_waitcnt lgkmcnt(0)
; #define SBAR() __builtin_amdgcn_sched_barrier(0)
; __device__ __forceinline__ void finishSM(f32x16& p0, f32x16& p1, float alpha, float& l_reg, bf16x8& pa0, bf16x8& pa1, bf16x8& pa2, bf16x8& pa3) {
; #pragma unroll
;   for (int r = 0; r < 16; ++r) p1[r] = __builtin_amdgcn_exp2f(p1[r]);
;   float ps = 0;
; #pragma unroll
;   for (int r = 0; r < 16; ++r) ps += p0[r];
; #pragma unroll
;   for (int r = 0; r < 16; ++r) ps += p1[r];
;   { auto rr = __builtin_amdgcn_permlane32_swap(__float_as_uint(ps), __float_as_uint(ps), false, false);
;     ps = __uint_as_float(rr[0]) + __uint_as_float(rr[1]); }
;   l_reg = l_reg * alpha + ps;
;     ...
;   PK4(p0, 0, pa0); PK4(p0, 8, pa1); PK4(p1, 0, pa2); PK4(p1, 8, pa3);
; template <int D0> __device__ __forceinline__ void pv_one(f32x16& od, int vb, bf16x8 pa0, bf16x8 pa1, bf16x8 pa2, bf16x8 pa3) {
;   const s16x4 l0 = tr_read<v_rd_off(D0, 0, 0)>(vb), h0 = tr_read<v_rd_off(D0, 0, 1)>(vb), l1 = tr_read<v_rd_off(D0, 1, 0)>(vb), h1 = tr_read<v_rd_off(D0, 1, 1)>(vb);
;   const s16x4 l2 = tr_read<v_rd_off(D0, 2, 0)>(vb), h2 = tr_read<v_rd_off(D0, 2, 1)>(vb), l3 = tr_read<v_rd_off(D0, 3, 0)>(vb), h3 = tr_read<v_rd_off(D0, 3, 1)>(vb);
;   asm volatile("s_waitcnt lgkmcnt(0)" ::: "memory"); SBAR();
;     ...
;   od = __builtin_amdgcn_mfma_f32_32x32x16_bf16(pa0, PK(l0, h0), od, 0, 0, 0);
;   od = __builtin_amdgcn_mfma_f32_32x32x16_bf16(pa1, PK(l1, h1), od, 0, 0, 0);
;   od = __builtin_amdgcn_mfma_f32_32x32x16_bf16(pa2, PK(l2, h2), od, 0, 0, 0);
;   od = __builtin_amdgcn_mfma_f32_32x32x16_bf16(pa3, PK(l3, h3), od, 0, 0, 0);
;     ...
; }
; __device__ __forceinline__ void pv_d0(f32x16* o, int vb, bf16x8 pa0, bf16x8 pa1, bf16x8 pa2, bf16x8 pa3) {
;   pv_one<0>(o[0], vb, pa0, pa1, pa2, pa3); pv_one<1>(o[1], vb, pa0, pa1, pa2, pa3); pv_one<2>(o[2], vb, pa0, pa1, pa2, pa3); pv_one<3>(o[3], vb, pa0, pa1, pa2, pa3);
	v_mfma_f32_32x32x16_bf16 v[96:111], v[6:9], v[128:131], v[96:111]
	v_exp_f32_e32 v6, v84
	v_add_f32_e32 v80, v2, v80
	v_exp_f32_e32 v7, v85
	v_add_f32_e32 v80, v3, v80
	v_exp_f32_e32 v8, v86
	v_add_f32_e32 v80, v4, v80
	v_exp_f32_e32 v9, v87
	v_add_f32_e32 v80, v5, v80
	v_add_f32_e32 v80, v6, v80
	v_add_f32_e32 v80, v7, v80
	v_add_f32_e32 v80, v8, v80
	v_add_f32_e32 v80, v9, v80
	v_add_f32_e32 v80, v10, v80
	v_add_f32_e32 v80, v11, v80
	v_add_f32_e32 v80, v12, v80
	v_add_f32_e32 v80, v13, v80
	v_add_f32_e32 v80, v176, v80
	v_add_f32_e32 v80, v177, v80
	v_add_f32_e32 v80, v178, v80
	v_add_f32_e32 v80, v95, v80
	v_mov_b32_e32 v81, v80
	s_nop 1
	v_permlane32_swap_b32_e32 v80, v81
	v_add_f32_e32 v80, v80, v81
	v_add_f32_e32 v226, v183, v80
	v_cvt_pk_bf16_f32 v80, v223, v225
	v_cvt_pk_bf16_f32 v81, v221, v224
	v_cvt_pk_bf16_f32 v82, v220, v222
	v_cvt_pk_bf16_f32 v83, v218, v219
	v_cvt_pk_bf16_f32 v84, v215, v217
	v_cvt_pk_bf16_f32 v85, v214, v216
	v_cvt_pk_bf16_f32 v86, v210, v213
	v_cvt_pk_bf16_f32 v87, v211, v212
	v_cvt_pk_bf16_f32 v88, v2, v3
	v_cvt_pk_bf16_f32 v89, v4, v5
	v_cvt_pk_bf16_f32 v90, v6, v7
	v_cvt_pk_bf16_f32 v91, v8, v9
	v_cvt_pk_bf16_f32 v95, v178, v95
	s_nop 0
	v_permlane32_swap_b32_e32 v80, v82
	v_permlane32_swap_b32_e32 v81, v83
	v_permlane32_swap_b32_e32 v84, v86
	v_permlane32_swap_b32_e32 v85, v87
	v_permlane32_swap_b32_e32 v88, v90
	v_permlane32_swap_b32_e32 v89, v91
	v_permlane32_swap_b32_e32 v93, v95
	s_add_i32 s100, s2, 2
	s_mul_i32 s100, s100, 0x60000
	v_add_u32_e32 v254, s100, v14
	v_add_u32_e32 v255, s100, v15
	global_load_dwordx4 v[2:5], v254, s[58:59]
	global_load_dwordx4 v[6:9], v255, s[58:59]
	global_load_dwordx4 v[10:13], v254, s[8:9]
	global_load_dwordx4 v[176:179], v255, s[8:9]
	v_add_u32_e32 v255, vcc_hi, v208
	ds_read_b64_tr_b16 v[210:211], v255 offset:0
	ds_read_b64_tr_b16 v[212:213], v255 offset:0x800
	ds_read_b64_tr_b16 v[214:215], v255 offset:0x1000
	ds_read_b64_tr_b16 v[216:217], v255 offset:0x1800
	ds_read_b64_tr_b16 v[218:219], v255 offset:0x2000
	ds_read_b64_tr_b16 v[220:221], v255 offset:0x2800
	ds_read_b64_tr_b16 v[222:223], v255 offset:0x3000
	ds_read_b64_tr_b16 v[224:225], v255 offset:0x3800
	s_waitcnt lgkmcnt(0)
	s_nop 0
	v_mfma_f32_32x32x16_bf16 v[16:31], v[80:83], v[210:213], v[16:31]
	ds_read_b64_tr_b16 v[210:211], v255 offset:0x200
	ds_read_b64_tr_b16 v[212:213], v255 offset:0xa00
	v_mfma_f32_32x32x16_bf16 v[16:31], v[84:87], v[214:217], v[16:31]
	ds_read_b64_tr_b16 v[214:215], v255 offset:0x1200
	ds_read_b64_tr_b16 v[216:217], v255 offset:0x1a00
	v_mfma_f32_32x32x16_bf16 v[16:31], v[88:91], v[218:221], v[16:31]
	ds_read_b64_tr_b16 v[218:219], v255 offset:0x2200
	ds_read_b64_tr_b16 v[220:221], v255 offset:0x2a00
	v_mfma_f32_32x32x16_bf16 v[16:31], v[92:95], v[222:225], v[16:31]
	ds_read_b64_tr_b16 v[222:223], v255 offset:0x3200
	ds_read_b64_tr_b16 v[224:225], v255 offset:0x3a00
	s_waitcnt lgkmcnt(0)
	v_mfma_f32_32x32x16_bf16 v[32:47], v[80:83], v[210:213], v[32:47]
	ds_read_b64_tr_b16 v[210:211], v255 offset:0x400
	ds_read_b64_tr_b16 v[212:213], v255 offset:0xc00
	v_mfma_f32_32x32x16_bf16 v[32:47], v[84:87], v[214:217], v[32:47]
	ds_read_b64_tr_b16 v[214:215], v255 offset:0x1400
	ds_read_b64_tr_b16 v[216:217], v255 offset:0x1c00
	v_mfma_f32_32x32x16_bf16 v[32:47], v[88:91], v[218:221], v[32:47]
	ds_read_b64_tr_b16 v[218:219], v255 offset:0x2400
	ds_read_b64_tr_b16 v[220:221], v255 offset:0x2c00
	v_mfma_f32_32x32x16_bf16 v[32:47], v[92:95], v[222:225], v[32:47]
	ds_read_b64_tr_b16 v[222:223], v255 offset:0x3400
	ds_read_b64_tr_b16 v[224:225], v255 offset:0x3c00
	s_waitcnt lgkmcnt(0)
	v_mfma_f32_32x32x16_bf16 v[48:63], v[80:83], v[210:213], v[48:63]
	ds_read_b64_tr_b16 v[210:211], v255 offset:0x600
	ds_read_b64_tr_b16 v[212:213], v255 offset:0xe00
	v_mfma_f32_32x32x16_bf16 v[48:63], v[84:87], v[214:217], v[48:63]
	ds_read_b64_tr_b16 v[214:215], v255 offset:0x1600
	ds_read_b64_tr_b16 v[216:217], v255 offset:0x1e00
	v_mfma_f32_32x32x16_bf16 v[48:63], v[88:91], v[218:221], v[48:63]
	ds_read_b64_tr_b16 v[218:219], v255 offset:0x2600
	ds_read_b64_tr_b16 v[220:221], v255 offset:0x2e00
	v_mfma_f32_32x32x16_bf16 v[48:63], v[92:95], v[222:225], v[48:63]
	ds_read_b64_tr_b16 v[222:223], v255 offset:0x3600
	ds_read_b64_tr_b16 v[224:225], v255 offset:0x3e00
	s_waitcnt lgkmcnt(0)
	v_mfma_f32_32x32x16_bf16 v[64:79], v[80:83], v[210:213], v[64:79]
	v_exp_f32_e32 v210, v112
	v_exp_f32_e32 v211, v113
	v_exp_f32_e32 v212, v114
	v_exp_f32_e32 v213, v115
	v_mfma_f32_32x32x16_bf16 v[64:79], v[84:87], v[214:217], v[64:79]
	v_exp_f32_e32 v214, v116
	v_exp_f32_e32 v215, v117
	v_exp_f32_e32 v216, v118
	v_exp_f32_e32 v217, v119
	v_mfma_f32_32x32x16_bf16 v[64:79], v[88:91], v[218:221], v[64:79]
	v_exp_f32_e32 v218, v120
	v_exp_f32_e32 v219, v121
	v_exp_f32_e32 v220, v122
	v_exp_f32_e32 v221, v123
	s_mov_b32 s100, vcc_lo
	s_mov_b32 vcc_lo, vcc_hi
	s_mov_b32 vcc_hi, s101
	s_mov_b32 s101, s100
	s_waitcnt lgkmcnt(0)
	s_barrier
; __device__ __forceinline__ void finishSM(f32x16& p0, f32x16& p1, float alpha, float& l_reg, bf16x8& pa0, bf16x8& pa1, bf16x8& pa2, bf16x8& pa3) {
; #pragma unroll
;   for (int r = 0; r < 16; ++r) p1[r] = __builtin_amdgcn_exp2f(p1[r]);
;   float ps = 0;
; #pragma unroll
;   for (int r = 0; r < 16; ++r) ps += p0[r];
; #pragma unroll
;   for (int r = 0; r < 16; ++r) ps += p1[r];
;   { auto rr = __builtin_amdgcn_permlane32_swap(__float_as_uint(ps), __float_as_uint(ps), false, false);
;     ps = __uint_as_float(rr[0]) + __uint_as_float(rr[1]); }
;   l_reg = l_reg * alpha + ps;
;     ...
;   PK4(p0, 0, pa0); PK4(p0, 8, pa1); PK4(p1, 0, pa2); PK4(p1, 8, pa3);
;     ...
; }
; #pragma unroll
;   for (int r = 0; r < 16; ++r) { p0[r] = init; p1[r] = init; }
; #pragma unroll
;   for (int d0 = 0; d0 < 8; ++d0) { int cb = (d0 * 16 + hi * 8) * 2;
;     bf16x8 b0 = *reinterpret_cast<const bf16x8*>((const char*)Ks + KSWZ(r32, cb));
;     bf16x8 b1 = *reinterpret_cast<const bf16x8*>((const char*)Ks + KSWZ(32 + r32, cb));
;     p0 = __builtin_amdgcn_mfma_f32_32x32x16_bf16(b0, qr[d0], p0, 0, 0, 0);
;     p1 = __builtin_amdgcn_mfma_f32_32x32x16_bf16(b1, qr[d0], p1, 0, 0, 0); }
; }
; __device__ __forceinline__ void qkt_c(f32x16& p0, f32x16& p1, const bf16* Ks, const bf16x8* qr, int r32, int hi) {
;   const f32x16 cinit = {};
; #pragma unroll
;   for (int d0 = 0; d0 < 8; ++d0) { int cb = (d0 * 16 + hi * 8) * 2;
;     bf16x8 b0 = *reinterpret_cast<const bf16x8*>((const char*)Ks + KSWZ(r32, cb));
;     bf16x8 b1 = *reinterpret_cast<const bf16x8*>((const char*)Ks + KSWZ(32 + r32, cb));
;     p0 = __builtin_amdgcn_mfma_f32_32x32x16_bf16(b0, qr[d0], d0 == 0 ? cinit : p0, 0, 0, 0);
;     p1 = __builtin_amdgcn_mfma_f32_32x32x16_bf16(b1, qr[d0], d0 == 0 ? cinit : p1, 0, 0, 0); }
; }
	ds_read_b128 v[80:83], v200 offset:32768
	ds_read_b128 v[84:87], v200 offset:40960
	v_mfma_f32_32x32x16_bf16 v[64:79], v[92:95], v[222:225], v[64:79]
	ds_read_b128 v[160:163], v201 offset:32768
	ds_read_b128 v[164:167], v201 offset:40960
	v_exp_f32_e32 v222, v124
	v_exp_f32_e32 v223, v125
	v_exp_f32_e32 v224, v126
	v_exp_f32_e32 v225, v127
	v_exp_f32_e32 v168, v104
	v_exp_f32_e32 v169, v105
	s_waitcnt lgkmcnt(3)
	v_mfma_f32_32x32x16_bf16 v[112:127], v[80:83], v[156:159], 0
	v_exp_f32_e32 v170, v106
	v_exp_f32_e32 v171, v107
	v_exp_f32_e32 v172, v108
	v_exp_f32_e32 v173, v109
	v_exp_f32_e32 v174, v110
	v_exp_f32_e32 v111, v111
	v_cvt_pk_bf16_f32 v108, v168, v169
	s_waitcnt lgkmcnt(2)
	v_mfma_f32_32x32x16_bf16 v[80:95], v[84:87], v[156:159], 0
	v_cvt_pk_bf16_f32 v109, v170, v171
	v_cvt_pk_bf16_f32 v110, v172, v173
	s_nop 0
	v_permlane32_swap_b32_e32 v108, v110
	s_waitcnt lgkmcnt(1)
	v_mfma_f32_32x32x16_bf16 v[112:127], v[160:163], v[152:155], v[112:127]
	s_waitcnt lgkmcnt(0)
	v_mfma_f32_32x32x16_bf16 v[80:95], v[164:167], v[152:155], v[80:95]
	ds_read_b128 v[160:163], v202 offset:32768
	ds_read_b128 v[164:167], v202 offset:40960
	s_waitcnt lgkmcnt(1)
	v_mfma_f32_32x32x16_bf16 v[112:127], v[160:163], v[148:151], v[112:127]
	s_waitcnt lgkmcnt(0)
	v_mfma_f32_32x32x16_bf16 v[80:95], v[164:167], v[148:151], v[80:95]
	ds_read_b128 v[160:163], v203 offset:32768
	ds_read_b128 v[164:167], v203 offset:40960
	v_add_u32_e32 v254, vcc_lo, v184
	v_add_u32_e32 v255, vcc_lo, v185
	s_waitcnt vmcnt(0)
	ds_write_b128 v254, v[2:5]
	s_waitcnt lgkmcnt(2)
	v_mfma_f32_32x32x16_bf16 v[112:127], v[160:163], v[144:147], v[112:127]
	s_waitcnt lgkmcnt(1)
	v_mfma_f32_32x32x16_bf16 v[80:95], v[164:167], v[144:147], v[80:95]
	ds_read_b128 v[160:163], v206 offset:32768
	ds_read_b128 v[164:167], v206 offset:40960
	ds_write_b128 v255, v[6:9]
	s_waitcnt lgkmcnt(2)
	v_mfma_f32_32x32x16_bf16 v[112:127], v[160:163], v[140:143], v[112:127]
	s_waitcnt lgkmcnt(1)
	v_mfma_f32_32x32x16_bf16 v[80:95], v[164:167], v[140:143], v[80:95]
	ds_read_b128 v[160:163], v204 offset:32768
	ds_read_b128 v[164:167], v204 offset:40960
	ds_write_b128 v198, v[10:13] offset:49152
	s_waitcnt lgkmcnt(2)
	v_mfma_f32_32x32x16_bf16 v[112:127], v[160:163], v[136:139], v[112:127]
	s_waitcnt lgkmcnt(1)
	v_mfma_f32_32x32x16_bf16 v[80:95], v[164:167], v[136:139], v[80:95]
	ds_read_b128 v[160:163], v205 offset:32768
	ds_read_b128 v[164:167], v205 offset:40960
	ds_write_b128 v199, v[176:179] offset:49152
	s_waitcnt lgkmcnt(2)
	v_mfma_f32_32x32x16_bf16 v[112:127], v[160:163], v[132:135], v[112:127]
	s_waitcnt lgkmcnt(1)
	v_mfma_f32_32x32x16_bf16 v[80:95], v[164:167], v[132:135], v[80:95]
	ds_read_b128 v[160:163], v207 offset:32768
	ds_read_b128 v[164:167], v207 offset:40960
	s_waitcnt lgkmcnt(1)
	v_mfma_f32_32x32x16_bf16 v[112:127], v[160:163], v[128:131], v[112:127]
	v_exp_f32_e32 v160, v96
	v_add_f32_e32 v96, 0, v210
	v_add_f32_e32 v96, v211, v96
	v_add_f32_e32 v96, v212, v96
	v_add_f32_e32 v96, v213, v96
	v_add_f32_e32 v96, v214, v96
	v_add_f32_e32 v96, v215, v96
	v_add_f32_e32 v96, v216, v96
	v_add_f32_e32 v96, v217, v96
	v_add_f32_e32 v96, v218, v96
	v_add_f32_e32 v96, v219, v96
	v_add_f32_e32 v96, v220, v96
	v_add_f32_e32 v96, v221, v96
	v_add_f32_e32 v96, v222, v96
	v_exp_f32_e32 v161, v97
	v_add_f32_e32 v96, v223, v96
	v_exp_f32_e32 v162, v98
	v_add_f32_e32 v96, v224, v96
	v_exp_f32_e32 v163, v99
	v_add_f32_e32 v96, v225, v96
	s_waitcnt lgkmcnt(0)
	v_mfma_f32_32x32x16_bf16 v[80:95], v[164:167], v[128:131], v[80:95]
	v_exp_f32_e32 v164, v100
	v_add_f32_e32 v96, v160, v96
	v_exp_f32_e32 v165, v101
	v_add_f32_e32 v96, v161, v96
	v_exp_f32_e32 v166, v102
	v_add_f32_e32 v96, v162, v96
	v_exp_f32_e32 v167, v103
	v_add_f32_e32 v96, v163, v96
	v_add_f32_e32 v96, v164, v96
	v_add_f32_e32 v96, v165, v96
	v_add_f32_e32 v96, v166, v96
	v_add_f32_e32 v96, v167, v96
	v_add_f32_e32 v96, v168, v96
	v_add_f32_e32 v96, v169, v96
	v_add_f32_e32 v96, v170, v96
	v_add_f32_e32 v96, v171, v96
	v_add_f32_e32 v96, v172, v96
	v_add_f32_e32 v96, v173, v96
	v_add_f32_e32 v96, v174, v96
	v_add_f32_e32 v96, v111, v96
	v_mov_b32_e32 v97, v96
	s_nop 1
	v_permlane32_swap_b32_e32 v96, v97
	v_add_f32_e32 v96, v96, v97
	v_add_f32_e32 v183, v226, v96
	v_cvt_pk_bf16_f32 v96, v210, v211
	v_cvt_pk_bf16_f32 v97, v212, v213
	v_cvt_pk_bf16_f32 v98, v214, v215
	v_cvt_pk_bf16_f32 v99, v216, v217
	v_cvt_pk_bf16_f32 v100, v218, v219
	v_cvt_pk_bf16_f32 v101, v220, v221
	v_cvt_pk_bf16_f32 v102, v222, v223
	v_cvt_pk_bf16_f32 v103, v224, v225
	v_cvt_pk_bf16_f32 v104, v160, v161
	v_cvt_pk_bf16_f32 v105, v162, v163
	v_cvt_pk_bf16_f32 v106, v164, v165
	v_cvt_pk_bf16_f32 v107, v166, v167
	v_cvt_pk_bf16_f32 v111, v174, v111
	s_nop 0
	v_permlane32_swap_b32_e32 v96, v98
	v_permlane32_swap_b32_e32 v97, v99
	v_permlane32_swap_b32_e32 v100, v102
	v_permlane32_swap_b32_e32 v101, v103
	v_permlane32_swap_b32_e32 v104, v106
	v_permlane32_swap_b32_e32 v105, v107
	v_permlane32_swap_b32_e32 v109, v111
	s_min_u32 s40, s2, 0xfc
	s_add_i32 s100, s40, 3
	s_mul_i32 s100, s100, 0x60000
	v_add_u32_e32 v254, s100, v14
	v_add_u32_e32 v255, s100, v15
	global_load_dwordx4 v[160:163], v254, s[58:59]
	global_load_dwordx4 v[164:167], v255, s[58:59]
	global_load_dwordx4 v[168:171], v254, s[8:9]
	global_load_dwordx4 v[172:175], v255, s[8:9]
	v_add_u32_e32 v255, vcc_hi, v208
	ds_read_b64_tr_b16 v[210:211], v255 offset:0
	ds_read_b64_tr_b16 v[212:213], v255 offset:0x800
	ds_read_b64_tr_b16 v[214:215], v255 offset:0x1000
	ds_read_b64_tr_b16 v[216:217], v255 offset:0x1800
	ds_read_b64_tr_b16 v[218:219], v255 offset:0x2000
	ds_read_b64_tr_b16 v[220:221], v255 offset:0x2800
	ds_read_b64_tr_b16 v[222:223], v255 offset:0x3000
	ds_read_b64_tr_b16 v[224:225], v255 offset:0x3800
	s_waitcnt lgkmcnt(0)
; #define SBAR() __builtin_amdgcn_sched_barrier(0)
; #define SWAIT() asm volatile("s_waitcnt vmcnt(4)" ::: "memory")
; template <int D0> __device__ __forceinline__ void pv_one(f32x16& od, int vb, bf16x8 pa0, bf16x8 pa1, bf16x8 pa2, bf16x8 pa3) {
;   const s16x4 l0 = tr_read<v_rd_off(D0, 0, 0)>(vb), h0 = tr_read<v_rd_off(D0, 0, 1)>(vb), l1 = tr_read<v_rd_off(D0, 1, 0)>(vb), h1 = tr_read<v_rd_off(D0, 1, 1)>(vb);
;   const s16x4 l2 = tr_read<v_rd_off(D0, 2, 0)>(vb), h2 = tr_read<v_rd_off(D0, 2, 1)>(vb), l3 = tr_read<v_rd_off(D0, 3, 0)>(vb), h3 = tr_read<v_rd_off(D0, 3, 1)>(vb);
;   asm volatile("s_waitcnt lgkmcnt(0)" ::: "memory"); SBAR();
;     ...
;   od = __builtin_amdgcn_mfma_f32_32x32x16_bf16(pa0, PK(l0, h0), od, 0, 0, 0);
;   od = __builtin_amdgcn_mfma_f32_32x32x16_bf16(pa1, PK(l1, h1), od, 0, 0, 0);
;   od = __builtin_amdgcn_mfma_f32_32x32x16_bf16(pa2, PK(l2, h2), od, 0, 0, 0);
;   od = __builtin_amdgcn_mfma_f32_32x32x16_bf16(pa3, PK(l3, h3), od, 0, 0, 0);
;     ...
; }
; __device__ __forceinline__ void pv_d0(f32x16* o, int vb, bf16x8 pa0, bf16x8 pa1, bf16x8 pa2, bf16x8 pa3) {
;   pv_one<0>(o[0], vb, pa0, pa1, pa2, pa3); pv_one<1>(o[1], vb, pa0, pa1, pa2, pa3); pv_one<2>(o[2], vb, pa0, pa1, pa2, pa3); pv_one<3>(o[3], vb, pa0, pa1, pa2, pa3);
; template <bool BANDED, bool FIXED> ...
;     ...
;   for (int j = 1; j + 1 < NT; j += 2) {
;     SBAR(); if (FIXED) qkt_c(pB0, pB1, (bf16*)((char*)K_lds + SHM_K), qr, r32, hi); else qkt(pB0, pB1, (bf16*)((char*)K_lds + SHM_K), qr, r32, hi, 0.f); MASK(pB0, pB1, j);
;     finishSM(pA0, pA1, alA, l_reg, pa0, pa1, pa2, pa3); SBAR();
;     SLOAD(SO, j + 2); SBAR();
;     pv_d0(o, vb0, pa0, pa1, pa2, pa3); partialSM<FIXED, !BANDED>(pB0, pB1, m_reg, mnB, alB);
;     __syncthreads(); SWAIT(); SWRITE(0, SE);
;     RESC(alB); __syncthreads();
;     SBAR(); if (FIXED) qkt_c(pA0, pA1, K_lds, qr, r32, hi); else qkt(pA0, pA1, K_lds, qr, r32, hi, 0.f); MASK(pA0, pA1, j + 1);
;     finishSM(pB0, pB1, alB, l_reg, pa0, pa1, pa2, pa3); SBAR();
;     SLOAD(SE, min(j + 3, NT - 1)); SBAR();
;     pv_d0(o, vb0 + (int)SHM_V, pa0, pa1, pa2, pa3); partialSM<FIXED, !BANDED>(pA0, pA1, m_reg, mnA, alA);
;     __syncthreads(); SWAIT(); SWRITE(1, SO);
;     RESC(alA); __syncthreads();
;   }
;   SBAR(); if (FIXED) qkt_c(pB0, pB1, (bf16*)((char*)K_lds + SHM_K), qr, r32, hi); else qkt(pB0, pB1, (bf16*)((char*)K_lds + SHM_K), qr, r32, hi, 0.f); MASK(pB0, pB1, NT - 1);
	s_nop 0
	v_mfma_f32_32x32x16_bf16 v[16:31], v[96:99], v[210:213], v[16:31]
	ds_read_b64_tr_b16 v[210:211], v255 offset:0x200
	ds_read_b64_tr_b16 v[212:213], v255 offset:0xa00
	v_mfma_f32_32x32x16_bf16 v[16:31], v[100:103], v[214:217], v[16:31]
	ds_read_b64_tr_b16 v[214:215], v255 offset:0x1200
	ds_read_b64_tr_b16 v[216:217], v255 offset:0x1a00
	v_mfma_f32_32x32x16_bf16 v[16:31], v[104:107], v[218:221], v[16:31]
	ds_read_b64_tr_b16 v[218:219], v255 offset:0x2200
	ds_read_b64_tr_b16 v[220:221], v255 offset:0x2a00
	v_mfma_f32_32x32x16_bf16 v[16:31], v[108:111], v[222:225], v[16:31]
	ds_read_b64_tr_b16 v[222:223], v255 offset:0x3200
	ds_read_b64_tr_b16 v[224:225], v255 offset:0x3a00
	s_waitcnt lgkmcnt(0)
	v_mfma_f32_32x32x16_bf16 v[32:47], v[96:99], v[210:213], v[32:47]
	ds_read_b64_tr_b16 v[210:211], v255 offset:0x400
	ds_read_b64_tr_b16 v[212:213], v255 offset:0xc00
	v_mfma_f32_32x32x16_bf16 v[32:47], v[100:103], v[214:217], v[32:47]
	ds_read_b64_tr_b16 v[214:215], v255 offset:0x1400
	ds_read_b64_tr_b16 v[216:217], v255 offset:0x1c00
	v_mfma_f32_32x32x16_bf16 v[32:47], v[104:107], v[218:221], v[32:47]
	ds_read_b64_tr_b16 v[218:219], v255 offset:0x2400
	ds_read_b64_tr_b16 v[220:221], v255 offset:0x2c00
	v_mfma_f32_32x32x16_bf16 v[32:47], v[108:111], v[222:225], v[32:47]
	ds_read_b64_tr_b16 v[222:223], v255 offset:0x3400
	ds_read_b64_tr_b16 v[224:225], v255 offset:0x3c00
	s_waitcnt lgkmcnt(0)
	v_mfma_f32_32x32x16_bf16 v[48:63], v[96:99], v[210:213], v[48:63]
	ds_read_b64_tr_b16 v[210:211], v255 offset:0x600
	ds_read_b64_tr_b16 v[212:213], v255 offset:0xe00
	v_mfma_f32_32x32x16_bf16 v[48:63], v[100:103], v[214:217], v[48:63]
	ds_read_b64_tr_b16 v[214:215], v255 offset:0x1600
	ds_read_b64_tr_b16 v[216:217], v255 offset:0x1e00
	v_mfma_f32_32x32x16_bf16 v[48:63], v[104:107], v[218:221], v[48:63]
	ds_read_b64_tr_b16 v[218:219], v255 offset:0x2600
	ds_read_b64_tr_b16 v[220:221], v255 offset:0x2e00
	v_mfma_f32_32x32x16_bf16 v[48:63], v[108:111], v[222:225], v[48:63]
	ds_read_b64_tr_b16 v[222:223], v255 offset:0x3600
	ds_read_b64_tr_b16 v[224:225], v255 offset:0x3e00
	s_waitcnt lgkmcnt(0)
	v_mfma_f32_32x32x16_bf16 v[64:79], v[96:99], v[210:213], v[64:79]
	v_exp_f32_e32 v210, v124
	v_exp_f32_e32 v213, v125
	v_exp_f32_e32 v211, v126
	v_exp_f32_e32 v212, v127
	v_mfma_f32_32x32x16_bf16 v[64:79], v[100:103], v[214:217], v[64:79]
	v_exp_f32_e32 v215, v120
	v_exp_f32_e32 v217, v121
	v_exp_f32_e32 v214, v122
	v_exp_f32_e32 v216, v123
	s_cmpk_gt_u32 s2, 0xfc
	v_mfma_f32_32x32x16_bf16 v[64:79], v[104:107], v[218:221], v[64:79]
	v_exp_f32_e32 v221, v114
	v_exp_f32_e32 v220, v116
	v_exp_f32_e32 v218, v118
	v_exp_f32_e32 v219, v119
	s_mov_b32 s100, vcc_lo
	s_mov_b32 vcc_lo, vcc_hi
	s_mov_b32 vcc_hi, s101
	s_mov_b32 s101, s100
	s_waitcnt lgkmcnt(0)
	s_barrier
	ds_read_b128 v[2:5], v200 offset:49152
	ds_read_b128 v[6:9], v200 offset:57344
	v_mfma_f32_32x32x16_bf16 v[64:79], v[108:111], v[222:225], v[64:79]
	v_exp_f32_e32 v223, v112
	v_exp_f32_e32 v225, v113
	v_exp_f32_e32 v224, v115
	v_exp_f32_e32 v222, v117
	s_cbranch_scc0 .LBB0_118
	v_add_u32_e32 v255, vcc_hi, v208
	v_add_u32_e32 v254, s101, v208
	v_exp_f32_e32 v12, v80
	v_exp_f32_e32 v13, v81
	v_exp_f32_e32 v14, v82
	s_waitcnt lgkmcnt(1)
	v_mfma_f32_32x32x16_bf16 v[112:127], v[2:5], v[156:159], 0
	v_exp_f32_e32 v15, v83
	v_exp_f32_e32 v80, v84
	v_exp_f32_e32 v81, v85
	v_exp_f32_e32 v82, v86
	v_exp_f32_e32 v83, v87
	v_exp_f32_e32 v84, v88
	v_exp_f32_e32 v85, v89
	s_waitcnt lgkmcnt(0)
	v_mfma_f32_32x32x16_bf16 v[96:111], v[6:9], v[156:159], 0
	ds_read_b128 v[2:5], v201 offset:49152
	ds_read_b128 v[6:9], v201 offset:57344
	v_exp_f32_e32 v86, v90
	v_exp_f32_e32 v87, v91
	v_exp_f32_e32 v88, v92
	v_exp_f32_e32 v89, v93
	v_exp_f32_e32 v90, v94
	v_exp_f32_e32 v91, v95
	s_waitcnt lgkmcnt(1)
	v_mfma_f32_32x32x16_bf16 v[112:127], v[2:5], v[152:155], v[112:127]
	v_cvt_pk_bf16_f32 v10, v210, v213
	v_cvt_pk_bf16_f32 v11, v211, v212
	s_waitcnt lgkmcnt(0)
	v_mfma_f32_32x32x16_bf16 v[96:111], v[6:9], v[152:155], v[96:111]
	ds_read_b128 v[2:5], v202 offset:49152
	ds_read_b128 v[6:9], v202 offset:57344
	s_waitcnt lgkmcnt(1)
	v_mfma_f32_32x32x16_bf16 v[112:127], v[2:5], v[148:151], v[112:127]
	s_waitcnt lgkmcnt(0)
	v_mfma_f32_32x32x16_bf16 v[96:111], v[6:9], v[148:151], v[96:111]
	ds_read_b128 v[2:5], v203 offset:49152
	ds_read_b128 v[6:9], v203 offset:57344
	s_waitcnt lgkmcnt(1)
	v_mfma_f32_32x32x16_bf16 v[112:127], v[2:5], v[144:147], v[112:127]
	s_waitcnt lgkmcnt(0)
	v_mfma_f32_32x32x16_bf16 v[96:111], v[6:9], v[144:147], v[96:111]
	ds_read_b128 v[2:5], v206 offset:49152
	ds_read_b128 v[6:9], v206 offset:57344
	s_waitcnt lgkmcnt(1)
	v_mfma_f32_32x32x16_bf16 v[112:127], v[2:5], v[140:143], v[112:127]
	s_waitcnt lgkmcnt(0)
	v_mfma_f32_32x32x16_bf16 v[96:111], v[6:9], v[140:143], v[96:111]
	ds_read_b128 v[2:5], v204 offset:49152
	ds_read_b128 v[6:9], v204 offset:57344
	s_waitcnt lgkmcnt(1)
	v_mfma_f32_32x32x16_bf16 v[112:127], v[2:5], v[136:139], v[112:127]
	s_waitcnt lgkmcnt(0)
	v_mfma_f32_32x32x16_bf16 v[96:111], v[6:9], v[136:139], v[96:111]
	ds_read_b128 v[2:5], v205 offset:49152
	ds_read_b128 v[6:9], v205 offset:57344
	s_waitcnt lgkmcnt(1)
	v_mfma_f32_32x32x16_bf16 v[112:127], v[2:5], v[132:135], v[112:127]
	s_waitcnt lgkmcnt(0)
	v_mfma_f32_32x32x16_bf16 v[96:111], v[6:9], v[132:135], v[96:111]
	ds_read_b128 v[2:5], v207 offset:49152
	ds_read_b128 v[6:9], v207 offset:57344
	s_waitcnt lgkmcnt(1)
; #define SBAR() __builtin_amdgcn_sched_barrier(0)
; __device__ __forceinline__ void finishSM(f32x16& p0, f32x16& p1, float alpha, float& l_reg, bf16x8& pa0, bf16x8& pa1, bf16x8& pa2, bf16x8& pa3) {
; #pragma unroll
;   for (int r = 0; r < 16; ++r) p1[r] = __builtin_amdgcn_exp2f(p1[r]);
;   float ps = 0;
; #pragma unroll
;   for (int r = 0; r < 16; ++r) ps += p0[r];
; #pragma unroll
;   for (int r = 0; r < 16; ++r) ps += p1[r];
;   { auto rr = __builtin_amdgcn_permlane32_swap(__float_as_uint(ps), __float_as_uint(ps), false, false);
;     ps = __uint_as_float(rr[0]) + __uint_as_float(rr[1]); }
;   l_reg = l_reg * alpha + ps;
;     ...
;   PK4(p0, 0, pa0); PK4(p0, 8, pa1); PK4(p1, 0, pa2); PK4(p1, 8, pa3);
; template <int D0> __device__ __forceinline__ void pv_one(f32x16& od, int vb, bf16x8 pa0, bf16x8 pa1, bf16x8 pa2, bf16x8 pa3) {
;   const s16x4 l0 = tr_read<v_rd_off(D0, 0, 0)>(vb), h0 = tr_read<v_rd_off(D0, 0, 1)>(vb), l1 = tr_read<v_rd_off(D0, 1, 0)>(vb), h1 = tr_read<v_rd_off(D0, 1, 1)>(vb);
;   const s16x4 l2 = tr_read<v_rd_off(D0, 2, 0)>(vb), h2 = tr_read<v_rd_off(D0, 2, 1)>(vb), l3 = tr_read<v_rd_off(D0, 3, 0)>(vb), h3 = tr_read<v_rd_off(D0, 3, 1)>(vb);
;   asm volatile("s_waitcnt lgkmcnt(0)" ::: "memory"); SBAR();
;     ...
;   od = __builtin_amdgcn_mfma_f32_32x32x16_bf16(pa0, PK(l0, h0), od, 0, 0, 0);
;   od = __builtin_amdgcn_mfma_f32_32x32x16_bf16(pa1, PK(l1, h1), od, 0, 0, 0);
;   od = __builtin_amdgcn_mfma_f32_32x32x16_bf16(pa2, PK(l2, h2), od, 0, 0, 0);
;   od = __builtin_amdgcn_mfma_f32_32x32x16_bf16(pa3, PK(l3, h3), od, 0, 0, 0);
;     ...
; }
; __device__ __forceinline__ void pv_d0(f32x16* o, int vb, bf16x8 pa0, bf16x8 pa1, bf16x8 pa2, bf16x8 pa3) {
;   pv_one<0>(o[0], vb, pa0, pa1, pa2, pa3); pv_one<1>(o[1], vb, pa0, pa1, pa2, pa3); pv_one<2>(o[2], vb, pa0, pa1, pa2, pa3); pv_one<3>(o[3], vb, pa0, pa1, pa2, pa3);
	v_mfma_f32_32x32x16_bf16 v[112:127], v[2:5], v[128:131], v[112:127]
	v_add_f32_e32 v2, 0, v223
	v_add_f32_e32 v2, v225, v2
	v_add_f32_e32 v2, v221, v2
	v_add_f32_e32 v2, v224, v2
	v_add_f32_e32 v2, v220, v2
	v_add_f32_e32 v2, v222, v2
	v_add_f32_e32 v2, v218, v2
	v_add_f32_e32 v2, v219, v2
	v_add_f32_e32 v2, v215, v2
	v_add_f32_e32 v2, v217, v2
	v_add_f32_e32 v2, v214, v2
	v_add_f32_e32 v2, v216, v2
	v_add_f32_e32 v2, v210, v2
	v_add_f32_e32 v2, v213, v2
	v_add_f32_e32 v2, v211, v2
	v_add_f32_e32 v2, v212, v2
	v_add_f32_e32 v2, v12, v2
	v_add_f32_e32 v2, v13, v2
	v_add_f32_e32 v2, v14, v2
	v_add_f32_e32 v2, v15, v2
	v_add_f32_e32 v2, v80, v2
	v_add_f32_e32 v2, v81, v2
	v_add_f32_e32 v2, v82, v2
	v_add_f32_e32 v2, v83, v2
	v_add_f32_e32 v2, v84, v2
	v_add_f32_e32 v2, v85, v2
	v_add_f32_e32 v2, v86, v2
	v_add_f32_e32 v2, v87, v2
	v_add_f32_e32 v2, v88, v2
	v_add_f32_e32 v2, v89, v2
	v_add_f32_e32 v2, v90, v2
	v_add_f32_e32 v2, v91, v2
	s_waitcnt lgkmcnt(0)
	v_mfma_f32_32x32x16_bf16 v[96:111], v[6:9], v[128:131], v[96:111]
	v_mov_b32_e32 v3, v2
	v_cvt_pk_bf16_f32 v4, v223, v225
	v_cvt_pk_bf16_f32 v5, v221, v224
	v_cvt_pk_bf16_f32 v6, v220, v222
	v_cvt_pk_bf16_f32 v7, v218, v219
	s_nop 1
	v_permlane32_swap_b32_e32 v2, v3
	v_permlane32_swap_b32_e32 v4, v6
	v_permlane32_swap_b32_e32 v5, v7
	v_cvt_pk_bf16_f32 v8, v215, v217
	v_cvt_pk_bf16_f32 v9, v214, v216
	v_cvt_pk_bf16_f32 v12, v12, v13
	v_cvt_pk_bf16_f32 v13, v14, v15
	v_cvt_pk_bf16_f32 v14, v80, v81
	v_cvt_pk_bf16_f32 v15, v82, v83
	v_cvt_pk_bf16_f32 v80, v84, v85
	v_cvt_pk_bf16_f32 v81, v86, v87
	v_cvt_pk_bf16_f32 v82, v88, v89
	v_cvt_pk_bf16_f32 v83, v90, v91
	s_nop 0
	v_permlane32_swap_b32_e32 v8, v10
	v_permlane32_swap_b32_e32 v9, v11
	v_permlane32_swap_b32_e32 v12, v14
	v_permlane32_swap_b32_e32 v13, v15
	v_permlane32_swap_b32_e32 v80, v82
	v_permlane32_swap_b32_e32 v81, v83
	ds_read_b64_tr_b16 v[84:85], v255 offset:0
	ds_read_b64_tr_b16 v[86:87], v255 offset:0x800
	ds_read_b64_tr_b16 v[88:89], v255 offset:0x1000
	ds_read_b64_tr_b16 v[90:91], v255 offset:0x1800
	ds_read_b64_tr_b16 v[92:93], v255 offset:0x2000
	ds_read_b64_tr_b16 v[94:95], v255 offset:0x2800
	ds_read_b64_tr_b16 v[128:129], v255 offset:0x3000
	ds_read_b64_tr_b16 v[130:131], v255 offset:0x3800
	s_waitcnt lgkmcnt(0)
	s_nop 0
	v_mfma_f32_32x32x16_bf16 v[16:31], v[4:7], v[84:87], v[16:31]
	ds_read_b64_tr_b16 v[84:85], v255 offset:0x200
	ds_read_b64_tr_b16 v[86:87], v255 offset:0xa00
	v_mfma_f32_32x32x16_bf16 v[16:31], v[8:11], v[88:91], v[16:31]
	ds_read_b64_tr_b16 v[88:89], v255 offset:0x1200
	ds_read_b64_tr_b16 v[90:91], v255 offset:0x1a00
	v_mfma_f32_32x32x16_bf16 v[16:31], v[12:15], v[92:95], v[16:31]
	ds_read_b64_tr_b16 v[92:93], v255 offset:0x2200
	ds_read_b64_tr_b16 v[94:95], v255 offset:0x2a00
	v_mfma_f32_32x32x16_bf16 v[16:31], v[80:83], v[128:131], v[16:31]
	ds_read_b64_tr_b16 v[128:129], v255 offset:0x3200
	ds_read_b64_tr_b16 v[130:131], v255 offset:0x3a00
	s_waitcnt lgkmcnt(0)
	v_mfma_f32_32x32x16_bf16 v[32:47], v[4:7], v[84:87], v[32:47]
	ds_read_b64_tr_b16 v[84:85], v255 offset:0x400
	ds_read_b64_tr_b16 v[86:87], v255 offset:0xc00
	v_mfma_f32_32x32x16_bf16 v[32:47], v[8:11], v[88:91], v[32:47]
	ds_read_b64_tr_b16 v[88:89], v255 offset:0x1400
	ds_read_b64_tr_b16 v[90:91], v255 offset:0x1c00
	v_mfma_f32_32x32x16_bf16 v[32:47], v[12:15], v[92:95], v[32:47]
	ds_read_b64_tr_b16 v[92:93], v255 offset:0x2400
	ds_read_b64_tr_b16 v[94:95], v255 offset:0x2c00
	v_mfma_f32_32x32x16_bf16 v[32:47], v[80:83], v[128:131], v[32:47]
	ds_read_b64_tr_b16 v[128:129], v255 offset:0x3400
	ds_read_b64_tr_b16 v[130:131], v255 offset:0x3c00
	s_waitcnt lgkmcnt(0)
	v_mfma_f32_32x32x16_bf16 v[48:63], v[4:7], v[84:87], v[48:63]
	ds_read_b64_tr_b16 v[84:85], v255 offset:0x600
	ds_read_b64_tr_b16 v[86:87], v255 offset:0xe00
	v_mfma_f32_32x32x16_bf16 v[48:63], v[8:11], v[88:91], v[48:63]
	ds_read_b64_tr_b16 v[88:89], v255 offset:0x1600
	ds_read_b64_tr_b16 v[90:91], v255 offset:0x1e00
	v_mfma_f32_32x32x16_bf16 v[48:63], v[12:15], v[92:95], v[48:63]
	ds_read_b64_tr_b16 v[92:93], v255 offset:0x2600
	ds_read_b64_tr_b16 v[94:95], v255 offset:0x2e00
	v_mfma_f32_32x32x16_bf16 v[48:63], v[80:83], v[128:131], v[48:63]
	ds_read_b64_tr_b16 v[128:129], v255 offset:0x3600
	ds_read_b64_tr_b16 v[130:131], v255 offset:0x3e00
	s_waitcnt lgkmcnt(0)
	v_mfma_f32_32x32x16_bf16 v[64:79], v[4:7], v[84:87], v[64:79]
	v_exp_f32_e32 v6, v112
	v_exp_f32_e32 v7, v113
	v_exp_f32_e32 v84, v126
	v_exp_f32_e32 v85, v127
	v_add_f32_e32 v4, 0, v6
	v_add_f32_e32 v4, v7, v4
	v_exp_f32_e32 v86, v96
	v_mfma_f32_32x32x16_bf16 v[64:79], v[8:11], v[88:91], v[64:79]
	v_exp_f32_e32 v8, v114
	v_exp_f32_e32 v9, v115
	v_exp_f32_e32 v10, v116
	v_exp_f32_e32 v11, v117
	v_add_f32_e32 v4, v8, v4
	v_add_f32_e32 v4, v9, v4
	v_add_f32_e32 v4, v10, v4
	v_mfma_f32_32x32x16_bf16 v[64:79], v[12:15], v[92:95], v[64:79]
	v_exp_f32_e32 v12, v118
	v_exp_f32_e32 v13, v119
	v_exp_f32_e32 v14, v120
	v_exp_f32_e32 v15, v121
	v_add_f32_e32 v4, v11, v4
	v_add_f32_e32 v4, v12, v4
	v_add_f32_e32 v4, v13, v4
	v_mfma_f32_32x32x16_bf16 v[64:79], v[80:83], v[128:131], v[64:79]
	v_exp_f32_e32 v80, v122
	v_exp_f32_e32 v81, v123
	v_exp_f32_e32 v82, v124
	v_add_f32_e32 v4, v14, v4
	v_exp_f32_e32 v83, v125
	v_add_f32_e32 v4, v15, v4
	v_add_f32_e32 v4, v80, v4
	v_add_f32_e32 v4, v81, v4
	v_add_f32_e32 v4, v82, v4
	v_exp_f32_e32 v87, v97
	v_add_f32_e32 v4, v83, v4
	v_exp_f32_e32 v88, v98
	v_add_f32_e32 v4, v84, v4
	v_exp_f32_e32 v89, v99
	v_add_f32_e32 v4, v85, v4
	v_exp_f32_e32 v90, v100
	v_add_f32_e32 v4, v86, v4
	v_exp_f32_e32 v91, v101
	v_add_f32_e32 v4, v87, v4
	v_exp_f32_e32 v92, v102
	v_add_f32_e32 v4, v88, v4
	v_exp_f32_e32 v93, v103
	v_add_f32_e32 v4, v89, v4
	v_exp_f32_e32 v94, v104
	v_add_f32_e32 v4, v90, v4
	v_exp_f32_e32 v95, v105
	v_add_f32_e32 v4, v91, v4
	v_exp_f32_e32 v96, v106
	v_add_f32_e32 v4, v92, v4
	v_exp_f32_e32 v97, v107
	v_add_f32_e32 v4, v93, v4
	v_exp_f32_e32 v98, v108
	v_add_f32_e32 v4, v94, v4
	v_exp_f32_e32 v99, v109
	v_add_f32_e32 v4, v95, v4
	v_exp_f32_e32 v100, v110
	v_add_f32_e32 v4, v96, v4
	v_exp_f32_e32 v101, v111
	v_add_f32_e32 v4, v97, v4
	v_add_f32_e32 v4, v98, v4
	v_add_f32_e32 v4, v99, v4
	v_add_f32_e32 v4, v100, v4
	v_add_f32_e32 v4, v101, v4
	v_mov_b32_e32 v5, v4
	s_nop 1
	v_permlane32_swap_b32_e32 v4, v5
	v_cvt_pk_bf16_f32 v6, v6, v7
	v_cvt_pk_bf16_f32 v7, v8, v9
	v_cvt_pk_bf16_f32 v8, v10, v11
	v_cvt_pk_bf16_f32 v9, v12, v13
	v_cvt_pk_bf16_f32 v10, v14, v15
	v_cvt_pk_bf16_f32 v11, v80, v81
	v_cvt_pk_bf16_f32 v12, v82, v83
	v_cvt_pk_bf16_f32 v13, v84, v85
	v_cvt_pk_bf16_f32 v80, v86, v87
	v_cvt_pk_bf16_f32 v81, v88, v89
	v_cvt_pk_bf16_f32 v82, v90, v91
	v_cvt_pk_bf16_f32 v83, v92, v93
	v_cvt_pk_bf16_f32 v84, v94, v95
	v_cvt_pk_bf16_f32 v85, v96, v97
	v_cvt_pk_bf16_f32 v86, v98, v99
	v_cvt_pk_bf16_f32 v87, v100, v101
	s_barrier
; #define SBAR() __builtin_amdgcn_sched_barrier(0)
; template <int D0> __device__ __forceinline__ void pv_one(f32x16& od, int vb, bf16x8 pa0, bf16x8 pa1, bf16x8 pa2, bf16x8 pa3) {
;   const s16x4 l0 = tr_read<v_rd_off(D0, 0, 0)>(vb), h0 = tr_read<v_rd_off(D0, 0, 1)>(vb), l1 = tr_read<v_rd_off(D0, 1, 0)>(vb), h1 = tr_read<v_rd_off(D0, 1, 1)>(vb);
;   const s16x4 l2 = tr_read<v_rd_off(D0, 2, 0)>(vb), h2 = tr_read<v_rd_off(D0, 2, 1)>(vb), l3 = tr_read<v_rd_off(D0, 3, 0)>(vb), h3 = tr_read<v_rd_off(D0, 3, 1)>(vb);
;   asm volatile("s_waitcnt lgkmcnt(0)" ::: "memory"); SBAR();
;     ...
;   od = __builtin_amdgcn_mfma_f32_32x32x16_bf16(pa0, PK(l0, h0), od, 0, 0, 0);
;   od = __builtin_amdgcn_mfma_f32_32x32x16_bf16(pa1, PK(l1, h1), od, 0, 0, 0);
;   od = __builtin_amdgcn_mfma_f32_32x32x16_bf16(pa2, PK(l2, h2), od, 0, 0, 0);
;   od = __builtin_amdgcn_mfma_f32_32x32x16_bf16(pa3, PK(l3, h3), od, 0, 0, 0);
;     ...
; }
; __device__ __forceinline__ void pv_d0(f32x16* o, int vb, bf16x8 pa0, bf16x8 pa1, bf16x8 pa2, bf16x8 pa3) {
;   pv_one<0>(o[0], vb, pa0, pa1, pa2, pa3); pv_one<1>(o[1], vb, pa0, pa1, pa2, pa3); pv_one<2>(o[2], vb, pa0, pa1, pa2, pa3); pv_one<3>(o[3], vb, pa0, pa1, pa2, pa3);
; template <bool BANDED, bool FIXED> ...
;     ...
;   finishSM(pB0, pB1, alB, l_reg, pa0, pa1, pa2, pa3); SBAR();
;   pv_d0(o, vb0 + (int)SHM_V, pa0, pa1, pa2, pa3);
;   if (!BANDED && wave >= 4) __builtin_amdgcn_s_setprio(0);
	v_permlane32_swap_b32_e32 v6, v8
	v_permlane32_swap_b32_e32 v7, v9
	v_permlane32_swap_b32_e32 v10, v12
	v_permlane32_swap_b32_e32 v11, v13
	v_permlane32_swap_b32_e32 v80, v82
	v_permlane32_swap_b32_e32 v81, v83
	v_permlane32_swap_b32_e32 v84, v86
	v_permlane32_swap_b32_e32 v85, v87
	ds_read_b64_tr_b16 v[88:89], v254 offset:0
	ds_read_b64_tr_b16 v[90:91], v254 offset:0x800
	ds_read_b64_tr_b16 v[92:93], v254 offset:0x1000
	ds_read_b64_tr_b16 v[94:95], v254 offset:0x1800
	ds_read_b64_tr_b16 v[96:97], v254 offset:0x2000
	ds_read_b64_tr_b16 v[98:99], v254 offset:0x2800
	ds_read_b64_tr_b16 v[100:101], v254 offset:0x3000
	ds_read_b64_tr_b16 v[102:103], v254 offset:0x3800
	s_waitcnt lgkmcnt(0)
	s_nop 0
	v_mfma_f32_32x32x16_bf16 v[16:31], v[6:9], v[88:91], v[16:31]
	ds_read_b64_tr_b16 v[88:89], v254 offset:0x200
	ds_read_b64_tr_b16 v[90:91], v254 offset:0xa00
	v_mfma_f32_32x32x16_bf16 v[16:31], v[10:13], v[92:95], v[16:31]
	ds_read_b64_tr_b16 v[92:93], v254 offset:0x1200
	ds_read_b64_tr_b16 v[94:95], v254 offset:0x1a00
	v_mfma_f32_32x32x16_bf16 v[16:31], v[80:83], v[96:99], v[16:31]
	ds_read_b64_tr_b16 v[96:97], v254 offset:0x2200
	ds_read_b64_tr_b16 v[98:99], v254 offset:0x2a00
	v_mfma_f32_32x32x16_bf16 v[16:31], v[84:87], v[100:103], v[16:31]
	ds_read_b64_tr_b16 v[100:101], v254 offset:0x3200
	ds_read_b64_tr_b16 v[102:103], v254 offset:0x3a00
	s_waitcnt lgkmcnt(0)
	v_mfma_f32_32x32x16_bf16 v[32:47], v[6:9], v[88:91], v[32:47]
	ds_read_b64_tr_b16 v[88:89], v254 offset:0x400
	ds_read_b64_tr_b16 v[90:91], v254 offset:0xc00
	v_mfma_f32_32x32x16_bf16 v[32:47], v[10:13], v[92:95], v[32:47]
	ds_read_b64_tr_b16 v[92:93], v254 offset:0x1400
	ds_read_b64_tr_b16 v[94:95], v254 offset:0x1c00
	v_mfma_f32_32x32x16_bf16 v[32:47], v[80:83], v[96:99], v[32:47]
	ds_read_b64_tr_b16 v[96:97], v254 offset:0x2400
	ds_read_b64_tr_b16 v[98:99], v254 offset:0x2c00
	v_mfma_f32_32x32x16_bf16 v[32:47], v[84:87], v[100:103], v[32:47]
	ds_read_b64_tr_b16 v[100:101], v254 offset:0x3400
	ds_read_b64_tr_b16 v[102:103], v254 offset:0x3c00
	s_waitcnt lgkmcnt(0)
	v_mfma_f32_32x32x16_bf16 v[48:63], v[6:9], v[88:91], v[48:63]
	ds_read_b64_tr_b16 v[88:89], v254 offset:0x600
	ds_read_b64_tr_b16 v[90:91], v254 offset:0xe00
	v_mfma_f32_32x32x16_bf16 v[48:63], v[10:13], v[92:95], v[48:63]
	ds_read_b64_tr_b16 v[92:93], v254 offset:0x1600
	ds_read_b64_tr_b16 v[94:95], v254 offset:0x1e00
	v_mfma_f32_32x32x16_bf16 v[48:63], v[80:83], v[96:99], v[48:63]
	ds_read_b64_tr_b16 v[96:97], v254 offset:0x2600
	ds_read_b64_tr_b16 v[98:99], v254 offset:0x2e00
	v_mfma_f32_32x32x16_bf16 v[48:63], v[84:87], v[100:103], v[48:63]
	ds_read_b64_tr_b16 v[100:101], v254 offset:0x3600
	ds_read_b64_tr_b16 v[102:103], v254 offset:0x3e00
	s_waitcnt lgkmcnt(0)
	v_mfma_f32_32x32x16_bf16 v[64:79], v[6:9], v[88:91], v[64:79]
	s_and_b64 vcc, exec, s[22:23]
	v_mfma_f32_32x32x16_bf16 v[64:79], v[10:13], v[92:95], v[64:79]
	v_mfma_f32_32x32x16_bf16 v[64:79], v[80:83], v[96:99], v[64:79]
	v_mfma_f32_32x32x16_bf16 v[64:79], v[84:87], v[100:103], v[64:79]
	s_cbranch_vccz .LBB0_121
	s_setprio 0

; __global__ void __launch_bounds__(NTHREADS) mega(Params p) {
;   extern __shared__ __attribute__((aligned(16))) char shm[];
	.amdhsa_kernel _Z4mega6Params
		.amdhsa_group_segment_fixed_size 0
		.amdhsa_private_segment_fixed_size 0
		.amdhsa_kernarg_size 384
		.amdhsa_user_sgpr_count 2
		.amdhsa_user_sgpr_dispatch_ptr 0
		.amdhsa_user_sgpr_queue_ptr 0
		.amdhsa_user_sgpr_kernarg_segment_ptr 1
		.amdhsa_user_sgpr_dispatch_id 0
		.amdhsa_user_sgpr_kernarg_preload_length 0
		.amdhsa_user_sgpr_kernarg_preload_offset 0
		.amdhsa_user_sgpr_private_segment_size 0
		.amdhsa_uses_dynamic_stack 0
		.amdhsa_enable_private_segment 0
		.amdhsa_system_sgpr_workgroup_id_x 1
		.amdhsa_system_sgpr_workgroup_id_y 0
		.amdhsa_system_sgpr_workgroup_id_z 0
		.amdhsa_system_sgpr_workgroup_info 0
		.amdhsa_system_vgpr_workitem_id 2
		.amdhsa_next_free_vgpr 256
		.amdhsa_next_free_sgpr 102
		.amdhsa_accum_offset 256
		.amdhsa_reserve_vcc 1
		.amdhsa_float_round_mode_32 0
		.amdhsa_float_round_mode_16_64 0
		.amdhsa_float_denorm_mode_32 3
		.amdhsa_float_denorm_mode_16_64 3
		.amdhsa_dx10_clamp 1
		.amdhsa_ieee_mode 1
		.amdhsa_fp16_overflow 0
		.amdhsa_tg_split 0
		.amdhsa_exception_fp_ieee_invalid_op 0
		.amdhsa_exception_fp_denorm_src 0
		.amdhsa_exception_fp_ieee_div_zero 0
		.amdhsa_exception_fp_ieee_overflow 0
		.amdhsa_exception_fp_ieee_underflow 0
		.amdhsa_exception_fp_ieee_inexact 0
		.amdhsa_exception_int_div_zero 0
	.end_amdhsa_kernel

; __global__ void __launch_bounds__(NTHREADS) mega(Params p) {
amdhsa.kernels:
  - .agpr_count:     0
    .args:
      - .offset:         0
        .size:           128
        .value_kind:     by_value
      - .offset:         128
        .size:           4
        .value_kind:     hidden_block_count_x
      - .offset:         132
        .size:           4
        .value_kind:     hidden_block_count_y
      - .offset:         136
        .size:           4
        .value_kind:     hidden_block_count_z
      - .offset:         140
        .size:           2
        .value_kind:     hidden_group_size_x
      - .offset:         142
        .size:           2
        .value_kind:     hidden_group_size_y
      - .offset:         144
        .size:           2
        .value_kind:     hidden_group_size_z
      - .offset:         146
        .size:           2
        .value_kind:     hidden_remainder_x
      - .offset:         148
        .size:           2
        .value_kind:     hidden_remainder_y
      - .offset:         150
        .size:           2
        .value_kind:     hidden_remainder_z
      - .offset:         168
        .size:           8
        .value_kind:     hidden_global_offset_x
      - .offset:         176
        .size:           8
        .value_kind:     hidden_global_offset_y
      - .offset:         184
        .size:           8
        .value_kind:     hidden_global_offset_z
      - .offset:         192
        .size:           2
        .value_kind:     hidden_grid_dims
      - .offset:         216
        .size:           8
        .value_kind:     hidden_multigrid_sync_arg
      - .offset:         248
        .size:           4
        .value_kind:     hidden_dynamic_lds_size
    .group_segment_fixed_size: 0
    .kernarg_segment_align: 8
    .kernarg_segment_size: 384
    .language:       OpenCL C
    .language_version:
      - 2
      - 0
    .max_flat_workgroup_size: 512
    .name:           _Z4mega6Params
    .private_segment_fixed_size: 0
    .sgpr_count:     108
    .sgpr_spill_count: 3
    .symbol:         _Z4mega6Params.kd
    .uniform_work_group_size: 1
    .uses_dynamic_stack: false
    .vgpr_count:     256
    .vgpr_spill_count: 0
    .wavefront_size: 64
